# stage-B work queue: the next queue index is claimed one item ahead (returning atomic issued when the previous one is consumed, no drain wait), so the claim round trip no longer sits between two items
# speedup vs baseline: 1.0011x; 1.0001x over previous
.LBB0_1151:
	s_or_b64 exec, exec, s[0:1]
	s_waitcnt vmcnt(25)
	v_mov_b32_e32 v1, v0
	s_barrier
	s_barrier
	s_nop 0
	v_cmp_eq_u32_e32 vcc, 0, v1
	s_and_saveexec_b64 s[0:1], vcc
	s_cbranch_execz .LBB0_1155
	s_mov_b64 s[6:7], exec
	v_mbcnt_lo_u32_b32 v1, s6, 0
	v_mbcnt_hi_u32_b32 v1, s7, v1
	v_cmp_eq_u32_e32 vcc, 0, v1
	s_and_saveexec_b64 s[4:5], vcc
	s_cbranch_execz .LBB0_1154
	s_lshl_b32 s2, s74, 6
	s_ashr_i32 s3, s2, 31
	s_lshl_b64 s[2:3], s[2:3], 2
	s_add_u32 s2, s94, s2
	s_addc_u32 s3, s95, s3
	s_bcnt1_i32_b64 s6, s[6:7]
	v_mov_b32_e32 v2, 0x2000
	v_mov_b32_e32 v3, s6
	v_mov_b32_e32 v254, v2
	global_atomic_add v2, v2, v3, s[2:3] sc0
	global_atomic_add v253, v254, v3, s[2:3] sc0

.LBB0_1159:
	s_or_b64 exec, exec, s[12:13]
	s_nop 0
	v_readfirstlane_b32 s12, v3
	v_mov_b32_e32 v3, s24
	s_nop 0
	v_add_u32_e32 v2, s12, v2
	ds_write_b32 v3, v2

.LBB0_1169:
	v_mov_b32_e32 v2, v0
	s_barrier
	s_nop 0
	v_cmp_eq_u32_e32 vcc, 0, v2
	s_and_saveexec_b64 s[4:5], vcc
	s_cbranch_execz .LBB0_1160
	s_mov_b64 s[14:15], exec
	v_mbcnt_lo_u32_b32 v2, s14, 0
	v_mbcnt_hi_u32_b32 v2, s15, v2
	v_cmp_eq_u32_e32 vcc, 0, v2
	s_and_saveexec_b64 s[12:13], vcc
	s_cbranch_execz .LBB0_1159
	s_bcnt1_i32_b64 s14, s[14:15]
	v_mov_b32_e32 v3, s14
	v_mov_b32_e32 v254, v3
	v_mov_b32_e32 v3, v253
	s_nop 0
	global_atomic_add v253, v97, v254, s[6:7] sc0
	s_branch .LBB0_1159

.LBB0_1176:
	s_or_b64 exec, exec, s[4:5]
	s_nop 0
	v_readfirstlane_b32 s4, v3
	v_mov_b32_e32 v3, s36
	s_nop 0
	v_add_u32_e32 v2, s4, v2
	ds_write_b32 v3, v2

.LBB0_1202:
	s_or_b64 exec, exec, s[0:1]
	v_mov_b32_e32 v2, v0
	s_barrier
	s_nop 0
	v_cmp_eq_u32_e32 vcc, 0, v2
	s_and_saveexec_b64 s[0:1], vcc
	s_cbranch_execz .LBB0_1177
	s_mov_b64 s[6:7], exec
	v_mbcnt_lo_u32_b32 v2, s6, 0
	v_mbcnt_hi_u32_b32 v2, s7, v2
	v_cmp_eq_u32_e32 vcc, 0, v2
	s_and_saveexec_b64 s[4:5], vcc
	s_cbranch_execz .LBB0_1176
	s_bcnt1_i32_b64 s6, s[6:7]
	v_mov_b32_e32 v3, s6
	v_mov_b32_e32 v254, v3
	v_mov_b32_e32 v3, v253
	s_nop 0
	global_atomic_add v253, v163, v254, s[54:55] sc0
	s_branch .LBB0_1176

.LBB0_1214:
	s_nop 1
	v_mov_b32_e32 v2, v0
	s_barrier
	s_nop 0
	v_cmp_eq_u32_e32 vcc, 0, v2
	s_and_saveexec_b64 s[0:1], vcc
	s_cbranch_execz .LBB0_1209
	s_mov_b64 s[6:7], exec
	v_mbcnt_lo_u32_b32 v2, s6, 0
	v_mbcnt_hi_u32_b32 v2, s7, v2
	v_cmp_eq_u32_e32 vcc, 0, v2
	s_and_saveexec_b64 s[4:5], vcc
	s_cbranch_execz .LBB0_1208
	s_bcnt1_i32_b64 s6, s[6:7]
	v_mov_b32_e32 v3, s6
	v_mov_b32_e32 v254, v3
	v_mov_b32_e32 v3, v253
	s_nop 0
	global_atomic_add v253, v163, v254, s[54:55] sc0
	s_branch .LBB0_1208

.LBB0_1219:
	s_or_b64 exec, exec, s[4:5]
	s_nop 0
	v_readfirstlane_b32 s4, v3
	v_mov_b32_e32 v3, s11
	s_nop 0
	v_add_u32_e32 v2, s4, v2
	ds_write_b32 v3, v2

.LBB0_1241:
	s_nop 1
	v_mov_b32_e32 v2, v0
	s_barrier
	s_nop 0
	v_cmp_eq_u32_e32 vcc, 0, v2
	s_and_saveexec_b64 s[0:1], vcc
	s_cbranch_execz .LBB0_1220
	s_mov_b64 s[6:7], exec
	v_mbcnt_lo_u32_b32 v2, s6, 0
	v_mbcnt_hi_u32_b32 v2, s7, v2
	v_cmp_eq_u32_e32 vcc, 0, v2
	s_and_saveexec_b64 s[4:5], vcc
	s_cbranch_execz .LBB0_1219
	s_bcnt1_i32_b64 s6, s[6:7]
	v_mov_b32_e32 v3, s6
	v_mov_b32_e32 v254, v3
	v_mov_b32_e32 v3, v253
	s_nop 0
	global_atomic_add v253, v159, v254, s[54:55] sc0
	s_branch .LBB0_1219

.LBB0_1247:
	s_or_b64 exec, exec, s[4:5]
	s_nop 0
	v_readfirstlane_b32 s4, v3
	v_mov_b32_e32 v3, s26
	s_nop 0
	v_add_u32_e32 v2, s4, v2
	ds_write_b32 v3, v2

.LBB0_1249:
	s_add_i32 s0, s14, 0xfffffb80
	s_ashr_i32 s1, s0, 31
	s_lshr_b32 s1, s1, 25
	s_add_i32 s1, s0, s1
	s_and_b32 s1, s1, 0xffffff80
	s_sub_i32 s4, s0, s1
	s_lshl_b32 s22, s4, 3
	s_ashr_i32 s23, s22, 31
	v_readfirstlane_b32 s5, v0
	s_add_u32 s0, s22, 0x4000
	s_addc_u32 s1, s23, 0
	s_lshr_b32 s5, s5, 4
	s_and_b32 s5, s5, 0xffffffc
	s_add_i32 s5, s5, 0
	s_lshl_b64 s[6:7], s[0:1], 11
	v_mov_b32_e32 v2, v0
	s_add_u32 s6, s33, s6
	s_addc_u32 s7, s34, s7
	v_ashrrev_i32_e32 v3, 31, v2
	v_lshl_add_u64 v[4:5], v[2:3], 1, s[6:7]
	s_barrier
	global_load_ushort v9, v[4:5], off offset:1024
	global_load_ushort v8, v[4:5], off
	v_and_b32_e32 v5, 63, v2
	v_cmp_eq_u32_e32 vcc, 0, v5
	v_mov_b32_e32 v4, 0
	s_waitcnt vmcnt(1)
	v_lshlrev_b32_e32 v16, 16, v9
	v_mul_f32_e32 v5, v16, v16
	s_nop 1
	v_mov_b32_dpp v5, v5 row_ror:8 row_mask:0xf bank_mask:0xf bound_ctrl:1
	v_fmac_f32_e32 v5, v16, v16
	s_nop 1
	v_add_f32_dpp v5, v5, v5 row_ror:4 row_mask:0xf bank_mask:0xf bound_ctrl:1
	s_nop 1
	v_add_f32_dpp v5, v5, v5 quad_perm:[2,3,0,1] row_mask:0xf bank_mask:0xf bound_ctrl:1
	s_nop 1
	v_add_f32_dpp v5, v5, v5 quad_perm:[1,0,3,2] row_mask:0xf bank_mask:0xf bound_ctrl:1
	s_nop 1
	v_mov_b32_dpp v4, v5 row_bcast:15 row_mask:0xa bank_mask:0xf
	v_add_f32_e32 v4, v5, v4
	v_mov_b32_e32 v5, 0
	s_nop 1
	v_mov_b32_dpp v5, v4 row_bcast:31 row_mask:0xc bank_mask:0xf
	v_add_f32_e32 v4, v4, v5
	s_nop 0
	v_readlane_b32 s10, v4, 63
	s_and_saveexec_b64 s[6:7], vcc
	v_mov_b32_e32 v4, s5
	v_mov_b32_e32 v5, s10
	ds_write_b32 v4, v5
	s_or_b64 exec, exec, s[6:7]
	s_add_u32 s6, s22, 0x4001
	s_addc_u32 s7, s23, 0
	s_lshl_b64 s[10:11], s[6:7], 11
	s_add_u32 s10, s33, s10
	s_addc_u32 s11, s34, s11
	v_lshl_add_u64 v[4:5], v[2:3], 1, s[10:11]
	global_load_ushort v10, v[4:5], off offset:1024
	global_load_ushort v9, v[4:5], off
	v_mov_b32_e32 v4, 0
	s_waitcnt vmcnt(1)
	v_lshlrev_b32_e32 v19, 16, v10
	v_mul_f32_e32 v5, v19, v19
	s_nop 1
	v_mov_b32_dpp v5, v5 row_ror:8 row_mask:0xf bank_mask:0xf bound_ctrl:1
	v_fmac_f32_e32 v5, v19, v19
	s_nop 1
	v_add_f32_dpp v5, v5, v5 row_ror:4 row_mask:0xf bank_mask:0xf bound_ctrl:1
	s_nop 1
	v_add_f32_dpp v5, v5, v5 quad_perm:[2,3,0,1] row_mask:0xf bank_mask:0xf bound_ctrl:1
	s_nop 1
	v_add_f32_dpp v5, v5, v5 quad_perm:[1,0,3,2] row_mask:0xf bank_mask:0xf bound_ctrl:1
	s_nop 1
	v_mov_b32_dpp v4, v5 row_bcast:15 row_mask:0xa bank_mask:0xf
	v_add_f32_e32 v4, v5, v4
	v_mov_b32_e32 v5, 0
	s_nop 1
	v_mov_b32_dpp v5, v4 row_bcast:31 row_mask:0xc bank_mask:0xf
	v_add_f32_e32 v4, v4, v5
	s_nop 0
	v_readlane_b32 s12, v4, 63
	s_and_saveexec_b64 s[10:11], vcc
	v_mov_b32_e32 v4, s5
	v_mov_b32_e32 v5, s12
	ds_write_b32 v4, v5 offset:32
	s_or_b64 exec, exec, s[10:11]
	s_add_u32 s10, s22, 0x4002
	s_addc_u32 s11, s23, 0
	s_lshl_b64 s[12:13], s[10:11], 11
	s_add_u32 s12, s33, s12
	s_addc_u32 s13, s34, s13
	v_lshl_add_u64 v[4:5], v[2:3], 1, s[12:13]
	global_load_ushort v11, v[4:5], off offset:1024
	global_load_ushort v10, v[4:5], off
	v_mov_b32_e32 v4, 0
	s_waitcnt vmcnt(1)
	v_lshlrev_b32_e32 v23, 16, v11
	v_mul_f32_e32 v5, v23, v23
	s_nop 1
	v_mov_b32_dpp v5, v5 row_ror:8 row_mask:0xf bank_mask:0xf bound_ctrl:1
	v_fmac_f32_e32 v5, v23, v23
	s_nop 1
	v_add_f32_dpp v5, v5, v5 row_ror:4 row_mask:0xf bank_mask:0xf bound_ctrl:1
	s_nop 1
	v_add_f32_dpp v5, v5, v5 quad_perm:[2,3,0,1] row_mask:0xf bank_mask:0xf bound_ctrl:1
	s_nop 1
	v_add_f32_dpp v5, v5, v5 quad_perm:[1,0,3,2] row_mask:0xf bank_mask:0xf bound_ctrl:1
	s_nop 1
	v_mov_b32_dpp v4, v5 row_bcast:15 row_mask:0xa bank_mask:0xf
	v_add_f32_e32 v4, v5, v4
	v_mov_b32_e32 v5, 0
	s_nop 1
	v_mov_b32_dpp v5, v4 row_bcast:31 row_mask:0xc bank_mask:0xf
	v_add_f32_e32 v4, v4, v5
	s_nop 0
	v_readlane_b32 s14, v4, 63
	s_and_saveexec_b64 s[12:13], vcc
	v_mov_b32_e32 v4, s5
	v_mov_b32_e32 v5, s14
	ds_write_b32 v4, v5 offset:64
	s_or_b64 exec, exec, s[12:13]
	s_add_u32 s12, s22, 0x4003
	s_addc_u32 s13, s23, 0
	s_lshl_b64 s[14:15], s[12:13], 11
	s_add_u32 s14, s33, s14
	s_addc_u32 s15, s34, s15
	v_lshl_add_u64 v[4:5], v[2:3], 1, s[14:15]
	global_load_ushort v11, v[4:5], off offset:1024
	global_load_ushort v12, v[4:5], off
	v_mov_b32_e32 v4, 0
	s_waitcnt vmcnt(1)
	v_lshlrev_b32_e32 v22, 16, v11
	v_mul_f32_e32 v5, v22, v22
	s_nop 1
	v_mov_b32_dpp v5, v5 row_ror:8 row_mask:0xf bank_mask:0xf bound_ctrl:1
	v_fmac_f32_e32 v5, v22, v22
	s_nop 1
	v_add_f32_dpp v5, v5, v5 row_ror:4 row_mask:0xf bank_mask:0xf bound_ctrl:1
	s_nop 1
	v_add_f32_dpp v5, v5, v5 quad_perm:[2,3,0,1] row_mask:0xf bank_mask:0xf bound_ctrl:1
	s_nop 1
	v_add_f32_dpp v5, v5, v5 quad_perm:[1,0,3,2] row_mask:0xf bank_mask:0xf bound_ctrl:1
	s_nop 1
	v_mov_b32_dpp v4, v5 row_bcast:15 row_mask:0xa bank_mask:0xf
	v_add_f32_e32 v4, v5, v4
	v_mov_b32_e32 v5, 0
	s_nop 1
	v_mov_b32_dpp v5, v4 row_bcast:31 row_mask:0xc bank_mask:0xf
	v_add_f32_e32 v4, v4, v5
	s_nop 0
	v_readlane_b32 s16, v4, 63
	s_and_saveexec_b64 s[14:15], vcc
	v_mov_b32_e32 v4, s5
	v_mov_b32_e32 v5, s16
	ds_write_b32 v4, v5 offset:96
	s_or_b64 exec, exec, s[14:15]
	s_add_u32 s14, s22, 0x4004
	s_addc_u32 s15, s23, 0
	s_lshl_b64 s[16:17], s[14:15], 11
	s_add_u32 s16, s33, s16
	s_addc_u32 s17, s34, s17
	v_lshl_add_u64 v[4:5], v[2:3], 1, s[16:17]
	global_load_ushort v13, v[4:5], off offset:1024
	global_load_ushort v11, v[4:5], off
	v_mov_b32_e32 v4, 0
	s_waitcnt vmcnt(1)
	v_lshlrev_b32_e32 v20, 16, v13
	v_mul_f32_e32 v5, v20, v20
	s_nop 1
	v_mov_b32_dpp v5, v5 row_ror:8 row_mask:0xf bank_mask:0xf bound_ctrl:1
	v_fmac_f32_e32 v5, v20, v20
	s_nop 1
	v_add_f32_dpp v5, v5, v5 row_ror:4 row_mask:0xf bank_mask:0xf bound_ctrl:1
	s_nop 1
	v_add_f32_dpp v5, v5, v5 quad_perm:[2,3,0,1] row_mask:0xf bank_mask:0xf bound_ctrl:1
	s_nop 1
	v_add_f32_dpp v5, v5, v5 quad_perm:[1,0,3,2] row_mask:0xf bank_mask:0xf bound_ctrl:1
	s_nop 1
	v_mov_b32_dpp v4, v5 row_bcast:15 row_mask:0xa bank_mask:0xf
	v_add_f32_e32 v4, v5, v4
	v_mov_b32_e32 v5, 0
	s_nop 1
	v_mov_b32_dpp v5, v4 row_bcast:31 row_mask:0xc bank_mask:0xf
	v_add_f32_e32 v4, v4, v5
	s_nop 0
	v_readlane_b32 s18, v4, 63
	s_and_saveexec_b64 s[16:17], vcc
	v_mov_b32_e32 v4, s5
	v_mov_b32_e32 v5, s18
	ds_write_b32 v4, v5 offset:128
	s_or_b64 exec, exec, s[16:17]
	s_add_u32 s16, s22, 0x4005
	s_addc_u32 s17, s23, 0
	s_lshl_b64 s[18:19], s[16:17], 11
	s_add_u32 s18, s33, s18
	s_addc_u32 s19, s34, s19
	v_lshl_add_u64 v[4:5], v[2:3], 1, s[18:19]
	global_load_ushort v14, v[4:5], off offset:1024
	global_load_ushort v13, v[4:5], off
	v_mov_b32_e32 v4, 0
	s_waitcnt vmcnt(1)
	v_lshlrev_b32_e32 v17, 16, v14
	v_mul_f32_e32 v5, v17, v17
	s_nop 1
	v_mov_b32_dpp v5, v5 row_ror:8 row_mask:0xf bank_mask:0xf bound_ctrl:1
	v_fmac_f32_e32 v5, v17, v17
	s_nop 1
	v_add_f32_dpp v5, v5, v5 row_ror:4 row_mask:0xf bank_mask:0xf bound_ctrl:1
	s_nop 1
	v_add_f32_dpp v5, v5, v5 quad_perm:[2,3,0,1] row_mask:0xf bank_mask:0xf bound_ctrl:1
	s_nop 1
	v_add_f32_dpp v5, v5, v5 quad_perm:[1,0,3,2] row_mask:0xf bank_mask:0xf bound_ctrl:1
	s_nop 1
	v_mov_b32_dpp v4, v5 row_bcast:15 row_mask:0xa bank_mask:0xf
	v_add_f32_e32 v4, v5, v4
	v_mov_b32_e32 v5, 0
	s_nop 1
	v_mov_b32_dpp v5, v4 row_bcast:31 row_mask:0xc bank_mask:0xf
	v_add_f32_e32 v4, v4, v5
	s_nop 0
	v_readlane_b32 s20, v4, 63
	s_and_saveexec_b64 s[18:19], vcc
	v_mov_b32_e32 v4, s5
	v_mov_b32_e32 v5, s20
	ds_write_b32 v4, v5 offset:160
	s_or_b64 exec, exec, s[18:19]
	s_add_u32 s18, s22, 0x4006
	s_addc_u32 s19, s23, 0
	s_lshl_b64 s[20:21], s[18:19], 11
	s_add_u32 s20, s33, s20
	s_addc_u32 s21, s34, s21
	v_lshl_add_u64 v[4:5], v[2:3], 1, s[20:21]
	global_load_ushort v15, v[4:5], off offset:1024
	global_load_ushort v14, v[4:5], off
	v_mov_b32_e32 v4, 0
	s_waitcnt vmcnt(1)
	v_lshlrev_b32_e32 v18, 16, v15
	v_mul_f32_e32 v5, v18, v18
	s_nop 1
	v_mov_b32_dpp v5, v5 row_ror:8 row_mask:0xf bank_mask:0xf bound_ctrl:1
	v_fmac_f32_e32 v5, v18, v18
	s_nop 1
	v_add_f32_dpp v5, v5, v5 row_ror:4 row_mask:0xf bank_mask:0xf bound_ctrl:1
	s_nop 1
	v_add_f32_dpp v5, v5, v5 quad_perm:[2,3,0,1] row_mask:0xf bank_mask:0xf bound_ctrl:1
	s_nop 1
	v_add_f32_dpp v5, v5, v5 quad_perm:[1,0,3,2] row_mask:0xf bank_mask:0xf bound_ctrl:1
	s_nop 1
	v_mov_b32_dpp v4, v5 row_bcast:15 row_mask:0xa bank_mask:0xf
	v_add_f32_e32 v4, v5, v4
	v_mov_b32_e32 v5, 0
	s_nop 1
	v_mov_b32_dpp v5, v4 row_bcast:31 row_mask:0xc bank_mask:0xf
	v_add_f32_e32 v4, v4, v5
	s_nop 0
	v_readlane_b32 s28, v4, 63
	s_and_saveexec_b64 s[20:21], vcc
	v_mov_b32_e32 v4, s5
	v_mov_b32_e32 v5, s28
	ds_write_b32 v4, v5 offset:192
	s_or_b64 exec, exec, s[20:21]
	s_add_u32 s20, s22, 0x4007
	s_addc_u32 s21, s23, 0
	s_lshl_b64 s[22:23], s[20:21], 11
	s_add_u32 s22, s33, s22
	s_addc_u32 s23, s34, s23
	v_lshl_add_u64 v[4:5], v[2:3], 1, s[22:23]
	global_load_ushort v21, v[4:5], off offset:1024
	global_load_ushort v15, v[4:5], off
	v_mov_b32_e32 v4, 0
	s_waitcnt vmcnt(1)
	v_lshlrev_b32_e32 v21, 16, v21
	v_mul_f32_e32 v5, v21, v21
	s_nop 1
	v_mov_b32_dpp v5, v5 row_ror:8 row_mask:0xf bank_mask:0xf bound_ctrl:1
	v_fmac_f32_e32 v5, v21, v21
	s_nop 1
	v_add_f32_dpp v5, v5, v5 row_ror:4 row_mask:0xf bank_mask:0xf bound_ctrl:1
	s_nop 1
	v_add_f32_dpp v5, v5, v5 quad_perm:[2,3,0,1] row_mask:0xf bank_mask:0xf bound_ctrl:1
	s_nop 1
	v_add_f32_dpp v5, v5, v5 quad_perm:[1,0,3,2] row_mask:0xf bank_mask:0xf bound_ctrl:1
	s_nop 1
	v_mov_b32_dpp v4, v5 row_bcast:15 row_mask:0xa bank_mask:0xf
	v_add_f32_e32 v4, v5, v4
	v_mov_b32_e32 v5, 0
	s_nop 1
	v_mov_b32_dpp v5, v4 row_bcast:31 row_mask:0xc bank_mask:0xf
	v_add_f32_e32 v4, v4, v5
	s_nop 0
	v_readlane_b32 s28, v4, 63
	s_and_saveexec_b64 s[22:23], vcc
	v_mov_b32_e32 v4, s5
	v_mov_b32_e32 v5, s28
	ds_write_b32 v4, v5 offset:224
	s_or_b64 exec, exec, s[22:23]
	v_readlane_b32 s36, v245, 26
	v_lshlrev_b64 v[4:5], 2, v[2:3]
	v_readlane_b32 s46, v245, 36
	v_readlane_b32 s47, v245, 37
	s_waitcnt lgkmcnt(0)
	s_barrier
	v_lshl_add_u64 v[24:25], s[46:47], 0, v[4:5]
	global_load_dword v36, v[24:25], off
	ds_read_b128 v[24:27], v1
	ds_read_b128 v[28:31], v1 offset:16
	s_ashr_i32 s5, s4, 31
	s_lshl_b64 s[4:5], s[4:5], 14
	s_add_u32 s22, s2, s4
	s_waitcnt lgkmcnt(1)
	v_add_f32_e32 v24, 0, v24
	v_add_f32_e32 v24, v24, v25
	v_add_f32_e32 v24, v24, v26
	v_add_f32_e32 v24, v24, v27
	s_waitcnt lgkmcnt(0)
	v_add_f32_e32 v24, v24, v28
	v_add_f32_e32 v24, v24, v29
	v_add_f32_e32 v24, v24, v30
	v_add_f32_e32 v24, v24, v31
	v_fmamk_f32 v24, v24, 0x3b000000, v6
	v_mul_f32_e32 v25, 0x4f800000, v24
	v_cmp_gt_f32_e32 vcc, s8, v24
	s_addc_u32 s23, s3, s5
	v_lshl_add_u64 v[4:5], s[22:23], 0, v[4:5]
	v_cndmask_b32_e32 v24, v24, v25, vcc
	v_sqrt_f32_e32 v25, v24
	v_readlane_b32 s48, v245, 38
	v_readlane_b32 s49, v245, 39
	v_readlane_b32 s50, v245, 40
	v_add_u32_e32 v26, -1, v25
	v_fma_f32 v27, -v26, v25, v24
	v_cmp_ge_f32_e64 s[4:5], 0, v27
	v_add_u32_e32 v27, 1, v25
	v_readlane_b32 s51, v245, 41
	v_cndmask_b32_e64 v26, v25, v26, s[4:5]
	v_fma_f32 v25, -v27, v25, v24
	v_cmp_lt_f32_e64 s[4:5], 0, v25
	v_lshlrev_b32_e32 v8, 16, v8
	v_lshlrev_b32_e32 v9, 16, v9
	v_cndmask_b32_e64 v25, v26, v27, s[4:5]
	v_mul_f32_e32 v26, 0x37800000, v25
	v_cndmask_b32_e32 v25, v25, v26, vcc
	v_cmp_class_f32_e32 vcc, v24, v7
	v_readlane_b32 s37, v245, 27
	v_readlane_b32 s38, v245, 28
	v_cndmask_b32_e32 v32, v25, v24, vcc
	ds_read_b128 v[24:27], v1 offset:32
	ds_read_b128 v[28:31], v1 offset:48
	v_div_scale_f32 v33, s[4:5], v32, v32, 1.0
	v_rcp_f32_e32 v34, v33
	s_waitcnt lgkmcnt(1)
	v_add_f32_e32 v24, 0, v24
	v_add_f32_e32 v24, v24, v25
	v_add_f32_e32 v24, v24, v26
	v_add_f32_e32 v24, v24, v27
	s_waitcnt lgkmcnt(0)
	v_add_f32_e32 v24, v24, v28
	v_add_f32_e32 v24, v24, v29
	v_add_f32_e32 v24, v24, v30
	v_add_f32_e32 v24, v24, v31
	v_fmamk_f32 v24, v24, 0x3b000000, v6
	v_mul_f32_e32 v25, 0x4f800000, v24
	v_cmp_gt_f32_e64 s[4:5], s8, v24
	v_fma_f32 v35, -v33, v34, 1.0
	v_fmac_f32_e32 v34, v35, v34
	v_cndmask_b32_e64 v24, v24, v25, s[4:5]
	v_sqrt_f32_e32 v25, v24
	v_div_scale_f32 v35, vcc, 1.0, v32, 1.0
	v_mul_f32_e32 v37, v35, v34
	v_fma_f32 v38, -v33, v37, v35
	v_fmac_f32_e32 v37, v38, v34
	v_add_u32_e32 v27, -1, v25
	v_fma_f32 v33, -v33, v37, v35
	v_fma_f32 v28, -v27, v25, v24
	v_div_fmas_f32 v26, v33, v34, v37
	v_cmp_ge_f32_e32 vcc, 0, v28
	v_add_u32_e32 v28, 1, v25
	v_div_fixup_f32 v26, v26, v32, 1.0
	v_cndmask_b32_e32 v27, v25, v27, vcc
	v_fma_f32 v25, -v28, v25, v24
	v_cmp_lt_f32_e32 vcc, 0, v25
	v_mul_f32_e32 v16, v26, v16
	v_readlane_b32 s39, v245, 29
	v_cndmask_b32_e32 v25, v27, v28, vcc
	v_mul_f32_e32 v27, 0x37800000, v25
	v_cndmask_b32_e64 v25, v25, v27, s[4:5]
	v_cmp_class_f32_e32 vcc, v24, v7
	s_waitcnt vmcnt(0)
	v_mul_f32_e32 v16, v36, v16
	global_store_dword v[4:5], v16, off
	v_cndmask_b32_e32 v32, v25, v24, vcc
	v_div_scale_f32 v28, s[4:5], v32, v32, 1.0
	v_rcp_f32_e32 v33, v28
	v_div_scale_f32 v29, vcc, 1.0, v32, 1.0
	v_readlane_b32 s40, v245, 30
	v_fma_f32 v24, -v28, v33, 1.0
	v_fmac_f32_e32 v33, v24, v33
	ds_read_b128 v[24:27], v1 offset:64
	v_mul_f32_e32 v34, v29, v33
	v_fma_f32 v30, -v28, v34, v29
	v_fmac_f32_e32 v34, v30, v33
	v_fma_f32 v35, -v28, v34, v29
	ds_read_b128 v[28:31], v1 offset:80
	s_waitcnt lgkmcnt(1)
	v_add_f32_e32 v24, 0, v24
	v_add_f32_e32 v24, v24, v25
	v_add_f32_e32 v24, v24, v26
	v_add_f32_e32 v24, v24, v27
	s_waitcnt lgkmcnt(0)
	v_add_f32_e32 v24, v24, v28
	v_add_f32_e32 v24, v24, v29
	v_add_f32_e32 v24, v24, v30
	v_add_f32_e32 v24, v24, v31
	v_fmamk_f32 v24, v24, 0x3b000000, v6
	v_mul_f32_e32 v25, 0x4f800000, v24
	v_cmp_gt_f32_e64 s[4:5], s8, v24
	v_div_fmas_f32 v26, v35, v33, v34
	v_div_fixup_f32 v26, v26, v32, 1.0
	v_cndmask_b32_e64 v24, v24, v25, s[4:5]
	v_sqrt_f32_e32 v25, v24
	v_mul_f32_e32 v19, v26, v19
	v_mul_f32_e32 v19, v36, v19
	global_store_dword v[4:5], v19, off offset:2048
	v_add_u32_e32 v27, -1, v25
	v_fma_f32 v28, -v27, v25, v24
	v_cmp_ge_f32_e32 vcc, 0, v28
	v_add_u32_e32 v28, 1, v25
	v_readlane_b32 s41, v245, 31
	v_cndmask_b32_e32 v27, v25, v27, vcc
	v_fma_f32 v25, -v28, v25, v24
	v_cmp_lt_f32_e32 vcc, 0, v25
	v_readlane_b32 s42, v245, 32
	v_readlane_b32 s43, v245, 33
	v_cndmask_b32_e32 v25, v27, v28, vcc
	v_mul_f32_e32 v27, 0x37800000, v25
	v_cndmask_b32_e64 v25, v25, v27, s[4:5]
	v_cmp_class_f32_e32 vcc, v24, v7
	v_readlane_b32 s44, v245, 34
	v_readlane_b32 s45, v245, 35
	v_cndmask_b32_e32 v28, v25, v24, vcc
	v_div_scale_f32 v24, s[4:5], v28, v28, 1.0
	v_rcp_f32_e32 v25, v24
	v_add_co_u32_e64 v32, s[4:5], s9, v4
	v_fma_f32 v26, -v24, v25, 1.0
	v_fmac_f32_e32 v25, v26, v25
	v_div_scale_f32 v26, vcc, 1.0, v28, 1.0
	v_mul_f32_e32 v27, v26, v25
	v_fma_f32 v29, -v24, v27, v26
	v_fmac_f32_e32 v27, v29, v25
	v_fma_f32 v24, -v24, v27, v26
	v_div_fmas_f32 v29, v24, v25, v27
	ds_read_b128 v[24:27], v1 offset:96
	v_div_fixup_f32 v28, v29, v28, 1.0
	v_mul_f32_e32 v23, v28, v23
	ds_read_b128 v[28:31], v1 offset:112
	v_mul_f32_e32 v42, v36, v23
	s_waitcnt lgkmcnt(1)
	v_add_f32_e32 v23, 0, v24
	v_add_f32_e32 v23, v23, v25
	v_add_f32_e32 v23, v23, v26
	v_add_f32_e32 v23, v23, v27
	s_waitcnt lgkmcnt(0)
	v_add_f32_e32 v23, v23, v28
	v_add_f32_e32 v23, v23, v29
	v_add_f32_e32 v23, v23, v30
	v_add_f32_e32 v23, v23, v31
	v_fmamk_f32 v23, v23, 0x3b000000, v6
	v_mul_f32_e32 v24, 0x4f800000, v23
	v_cmp_gt_f32_e32 vcc, s8, v23
	v_addc_co_u32_e64 v33, s[4:5], 0, v5, s[4:5]
	s_nop 0
	v_cndmask_b32_e32 v23, v23, v24, vcc
	v_sqrt_f32_e32 v24, v23
	s_nop 0
	v_add_u32_e32 v25, -1, v24
	v_fma_f32 v26, -v25, v24, v23
	v_cmp_ge_f32_e64 s[4:5], 0, v26
	v_add_u32_e32 v26, 1, v24
	s_nop 0
	v_cndmask_b32_e64 v25, v24, v25, s[4:5]
	v_fma_f32 v24, -v26, v24, v23
	v_cmp_lt_f32_e64 s[4:5], 0, v24
	s_nop 1
	v_cndmask_b32_e64 v24, v25, v26, s[4:5]
	v_mul_f32_e32 v25, 0x37800000, v24
	v_cndmask_b32_e32 v24, v24, v25, vcc
	v_cmp_class_f32_e32 vcc, v23, v7
	s_nop 1
	v_cndmask_b32_e32 v23, v24, v23, vcc
	v_div_scale_f32 v28, s[4:5], v23, v23, 1.0
	v_rcp_f32_e32 v37, v28
	v_add_co_u32_e32 v34, vcc, s24, v4
	v_fma_f32 v24, -v28, v37, 1.0
	s_nop 0
	v_addc_co_u32_e32 v35, vcc, 0, v5, vcc
	v_fmac_f32_e32 v37, v24, v37
	v_div_scale_f32 v29, vcc, 1.0, v23, 1.0
	ds_read_b128 v[24:27], v1 offset:128
	v_mul_f32_e32 v38, v29, v37
	v_fma_f32 v30, -v28, v38, v29
	v_fmac_f32_e32 v38, v30, v37
	v_fma_f32 v39, -v28, v38, v29
	ds_read_b128 v[28:31], v1 offset:144
	s_waitcnt lgkmcnt(1)
	v_add_f32_e32 v24, 0, v24
	v_add_f32_e32 v24, v24, v25
	v_add_f32_e32 v24, v24, v26
	v_add_f32_e32 v24, v24, v27
	s_waitcnt lgkmcnt(0)
	v_add_f32_e32 v24, v24, v28
	v_add_f32_e32 v24, v24, v29
	v_add_f32_e32 v24, v24, v30
	v_add_f32_e32 v24, v24, v31
	v_fmamk_f32 v24, v24, 0x3b000000, v6
	v_mul_f32_e32 v25, 0x4f800000, v24
	v_cmp_gt_f32_e64 s[4:5], s8, v24
	v_div_fmas_f32 v26, v39, v37, v38
	v_div_fixup_f32 v23, v26, v23, 1.0
	v_cndmask_b32_e64 v24, v24, v25, s[4:5]
	v_sqrt_f32_e32 v25, v24
	v_mul_f32_e32 v22, v23, v22
	v_mul_f32_e32 v43, v36, v22
	global_store_dword v[32:33], v43, off offset:2048
	v_add_u32_e32 v26, -1, v25
	v_fma_f32 v27, -v26, v25, v24
	v_cmp_ge_f32_e32 vcc, 0, v27
	v_add_u32_e32 v27, 1, v25
	global_store_dword v[34:35], v42, off offset:-4096
	v_cndmask_b32_e32 v26, v25, v26, vcc
	v_fma_f32 v25, -v27, v25, v24
	v_cmp_lt_f32_e32 vcc, 0, v25
	s_nop 1
	v_cndmask_b32_e32 v25, v26, v27, vcc
	v_mul_f32_e32 v26, 0x37800000, v25
	v_cndmask_b32_e64 v25, v25, v26, s[4:5]
	v_cmp_class_f32_e32 vcc, v24, v7
	s_nop 1
	v_cndmask_b32_e32 v30, v25, v24, vcc
	v_div_scale_f32 v26, s[4:5], v30, v30, 1.0
	v_rcp_f32_e32 v31, v26
	v_div_scale_f32 v27, vcc, 1.0, v30, 1.0
	v_fma_f32 v22, -v26, v31, 1.0
	v_fmac_f32_e32 v31, v22, v31
	ds_read_b128 v[22:25], v1 offset:160
	v_mul_f32_e32 v32, v27, v31
	v_fma_f32 v28, -v26, v32, v27
	v_fmac_f32_e32 v32, v28, v31
	v_fma_f32 v33, -v26, v32, v27
	ds_read_b128 v[26:29], v1 offset:176
	s_waitcnt lgkmcnt(1)
	v_add_f32_e32 v22, 0, v22
	v_add_f32_e32 v22, v22, v23
	v_add_f32_e32 v22, v22, v24
	v_add_f32_e32 v22, v22, v25
	s_waitcnt lgkmcnt(0)
	v_add_f32_e32 v22, v22, v26
	v_add_f32_e32 v22, v22, v27
	v_add_f32_e32 v22, v22, v28
	v_add_f32_e32 v22, v22, v29
	v_fmamk_f32 v22, v22, 0x3b000000, v6
	v_mul_f32_e32 v23, 0x4f800000, v22
	v_cmp_gt_f32_e64 s[4:5], s8, v22
	v_div_fmas_f32 v24, v33, v31, v32
	v_div_fixup_f32 v24, v24, v30, 1.0
	v_cndmask_b32_e64 v22, v22, v23, s[4:5]
	v_sqrt_f32_e32 v23, v22
	v_mul_f32_e32 v20, v24, v20
	v_mul_f32_e32 v44, v36, v20
	global_store_dword v[34:35], v44, off
	v_add_u32_e32 v25, -1, v23
	v_fma_f32 v26, -v25, v23, v22
	v_cmp_ge_f32_e32 vcc, 0, v26
	v_add_u32_e32 v26, 1, v23
	s_nop 0
	v_cndmask_b32_e32 v25, v23, v25, vcc
	v_fma_f32 v23, -v26, v23, v22
	v_cmp_lt_f32_e32 vcc, 0, v23
	s_nop 1
	v_cndmask_b32_e32 v23, v25, v26, vcc
	v_mul_f32_e32 v25, 0x37800000, v23
	v_cndmask_b32_e64 v23, v23, v25, s[4:5]
	v_cmp_class_f32_e32 vcc, v22, v7
	s_nop 1
	v_cndmask_b32_e32 v30, v23, v22, vcc
	v_div_scale_f32 v26, s[4:5], v30, v30, 1.0
	v_rcp_f32_e32 v31, v26
	ds_read_b128 v[22:25], v1 offset:192
	v_fma_f32 v20, -v26, v31, 1.0
	v_fmac_f32_e32 v31, v20, v31
	v_div_scale_f32 v20, vcc, 1.0, v30, 1.0
	v_mul_f32_e32 v32, v20, v31
	v_fma_f32 v27, -v26, v32, v20
	v_fmac_f32_e32 v32, v27, v31
	v_fma_f32 v20, -v26, v32, v20
	ds_read_b128 v[26:29], v1 offset:208
	s_waitcnt lgkmcnt(1)
	v_add_f32_e32 v22, 0, v22
	v_add_f32_e32 v22, v22, v23
	v_add_f32_e32 v22, v22, v24
	v_add_f32_e32 v22, v22, v25
	s_waitcnt lgkmcnt(0)
	v_add_f32_e32 v22, v22, v26
	v_add_f32_e32 v22, v22, v27
	v_add_f32_e32 v22, v22, v28
	v_add_f32_e32 v22, v22, v29
	v_fmamk_f32 v22, v22, 0x3b000000, v6
	v_mul_f32_e32 v23, 0x4f800000, v22
	v_cmp_gt_f32_e64 s[4:5], s8, v22
	v_div_fmas_f32 v20, v20, v31, v32
	v_div_fixup_f32 v20, v20, v30, 1.0
	v_cndmask_b32_e64 v22, v22, v23, s[4:5]
	v_sqrt_f32_e32 v23, v22
	v_mul_f32_e32 v17, v20, v17
	v_mul_f32_e32 v17, v36, v17
	global_store_dword v[34:35], v17, off offset:2048
	v_add_u32_e32 v24, -1, v23
	v_fma_f32 v25, -v24, v23, v22
	v_cmp_ge_f32_e32 vcc, 0, v25
	v_add_u32_e32 v25, 1, v23
	s_nop 0
	v_cndmask_b32_e32 v24, v23, v24, vcc
	v_fma_f32 v23, -v25, v23, v22
	v_cmp_lt_f32_e32 vcc, 0, v23
	s_nop 1
	v_cndmask_b32_e32 v23, v24, v25, vcc
	v_mul_f32_e32 v24, 0x37800000, v23
	v_cndmask_b32_e64 v23, v23, v24, s[4:5]
	v_cmp_class_f32_e32 vcc, v22, v7
	s_nop 1
	v_cndmask_b32_e32 v30, v23, v22, vcc
	v_div_scale_f32 v26, s[4:5], v30, v30, 1.0
	v_rcp_f32_e32 v27, v26
	s_nop 0
	v_fma_f32 v20, -v26, v27, 1.0
	v_fmac_f32_e32 v27, v20, v27
	v_div_scale_f32 v20, vcc, 1.0, v30, 1.0
	v_mul_f32_e32 v28, v20, v27
	v_fma_f32 v22, -v26, v28, v20
	v_fmac_f32_e32 v28, v22, v27
	ds_read_b128 v[22:25], v1 offset:224
	v_fma_f32 v20, -v26, v28, v20
	v_div_fmas_f32 v20, v20, v27, v28
	ds_read_b128 v[26:29], v1 offset:240
	v_div_fixup_f32 v20, v20, v30, 1.0
	s_waitcnt lgkmcnt(1)
	v_add_f32_e32 v22, 0, v22
	v_add_f32_e32 v22, v22, v23
	v_add_f32_e32 v22, v22, v24
	v_add_f32_e32 v22, v22, v25
	s_waitcnt lgkmcnt(0)
	v_add_f32_e32 v22, v22, v26
	v_add_f32_e32 v22, v22, v27
	v_add_f32_e32 v22, v22, v28
	v_add_f32_e32 v22, v22, v29
	v_fmamk_f32 v22, v22, 0x3b000000, v6
	v_mul_f32_e32 v23, 0x4f800000, v22
	v_cmp_gt_f32_e32 vcc, s8, v22
	v_mul_f32_e32 v18, v20, v18
	v_mul_f32_e32 v18, v36, v18
	v_cndmask_b32_e32 v22, v22, v23, vcc
	v_sqrt_f32_e32 v23, v22
	s_nop 0
	v_add_u32_e32 v20, -1, v23
	v_fma_f32 v24, -v20, v23, v22
	v_cmp_ge_f32_e64 s[4:5], 0, v24
	v_add_u32_e32 v24, 1, v23
	s_nop 0
	v_cndmask_b32_e64 v20, v23, v20, s[4:5]
	v_fma_f32 v23, -v24, v23, v22
	v_cmp_lt_f32_e64 s[4:5], 0, v23
	s_nop 1
	v_cndmask_b32_e64 v20, v20, v24, s[4:5]
	v_mul_f32_e32 v23, 0x37800000, v20
	v_cndmask_b32_e32 v20, v20, v23, vcc
	v_cmp_class_f32_e32 vcc, v22, v7
	s_nop 1
	v_cndmask_b32_e32 v20, v20, v22, vcc
	v_div_scale_f32 v22, s[4:5], v20, v20, 1.0
	v_rcp_f32_e32 v23, v22
	v_add_co_u32_e32 v4, vcc, s25, v4
	v_fma_f32 v24, -v22, v23, 1.0
	s_nop 0
	v_addc_co_u32_e32 v5, vcc, 0, v5, vcc
	v_fmac_f32_e32 v23, v24, v23
	v_div_scale_f32 v24, vcc, 1.0, v20, 1.0
	v_mul_f32_e32 v25, v24, v23
	v_fma_f32 v26, -v22, v25, v24
	v_fmac_f32_e32 v25, v26, v23
	v_fma_f32 v22, -v22, v25, v24
	v_div_fmas_f32 v22, v22, v23, v25
	v_div_fixup_f32 v20, v22, v20, 1.0
	v_mul_f32_e32 v20, v20, v21
	v_mul_f32_e32 v35, v36, v20
	global_store_dword v[4:5], v18, off
	global_store_dword v[4:5], v35, off offset:2048
	v_ashrrev_i32_e32 v4, 7, v2
	v_and_b32_e32 v20, 0xffffff80, v2
	v_ashrrev_i32_e32 v5, 31, v4
	v_lshlrev_b64 v[4:5], 16, v[4:5]
	v_ashrrev_i32_e32 v21, 31, v20
	v_lshl_add_u64 v[36:37], s[48:49], 0, v[4:5]
	v_lshl_add_u64 v[4:5], v[20:21], 2, s[50:51]
	global_load_dwordx4 v[20:23], v[4:5], off
	global_load_dword v40, v[36:37], off
	global_load_dwordx2 v[38:39], v[36:37], off offset:512
	global_load_dwordx3 v[32:34], v[36:37], off offset:1024
	global_load_dwordx4 v[24:27], v[36:37], off offset:1536
	global_load_dwordx4 v[28:31], v[4:5], off offset:16
	v_lshlrev_b32_e32 v5, 16, v10
	v_lshlrev_b32_e32 v4, 16, v12
	s_waitcnt vmcnt(4)
	v_fma_f32 v10, v16, v40, v20
	v_mul_f32_e32 v8, v10, v8
	v_cvt_pk_bf16_f32 v8, v8, s0
	s_lshl_b64 s[0:1], s[0:1], 12
	s_add_u32 s0, s82, s0
	s_addc_u32 s1, s83, s1
	v_lshlrev_b64 v[40:41], 1, v[2:3]
	v_lshl_add_u64 v[2:3], s[0:1], 0, v[40:41]
	global_store_short v[2:3], v8, off offset:2048
	s_waitcnt vmcnt(4)
	v_fma_f32 v2, v16, v38, v21
	v_fmac_f32_e32 v2, v19, v39
	v_mul_f32_e32 v2, v2, v9
	v_cvt_pk_bf16_f32 v8, v2, s0
	s_lshl_b64 s[0:1], s[6:7], 12
	s_add_u32 s0, s82, s0
	s_addc_u32 s1, s83, s1
	v_lshl_add_u64 v[2:3], s[0:1], 0, v[40:41]
	global_store_short v[2:3], v8, off offset:2048
	s_waitcnt vmcnt(4)
	v_fma_f32 v2, v16, v32, v22
	v_fmac_f32_e32 v2, v19, v33
	v_fmac_f32_e32 v2, v42, v34
	v_mul_f32_e32 v2, v2, v5
	v_cvt_pk_bf16_f32 v5, v2, s0
	s_lshl_b64 s[0:1], s[10:11], 12
	s_waitcnt vmcnt(3)
	v_fmac_f32_e32 v23, v16, v24
	s_add_u32 s0, s82, s0
	v_fmac_f32_e32 v23, v19, v25
	s_addc_u32 s1, s83, s1
	v_fmac_f32_e32 v23, v42, v26
	v_lshl_add_u64 v[2:3], s[0:1], 0, v[40:41]
	v_fmac_f32_e32 v23, v43, v27
	global_store_short v[2:3], v5, off offset:2048
	v_mul_f32_e32 v2, v23, v4
	v_cvt_pk_bf16_f32 v4, v2, s0
	s_lshl_b64 s[0:1], s[12:13], 12
	s_add_u32 s0, s82, s0
	s_addc_u32 s1, s83, s1
	v_lshl_add_u64 v[2:3], s[0:1], 0, v[40:41]
	global_store_short v[2:3], v4, off offset:2048
	global_load_dwordx4 v[2:5], v[36:37], off offset:2048
	s_nop 0
	global_load_dword v8, v[36:37], off offset:2064
	v_lshlrev_b32_e32 v9, 16, v11
	v_lshlrev_b32_e32 v10, 16, v13
	v_lshlrev_b32_e32 v11, 16, v14
	v_lshlrev_b32_e32 v14, 16, v15
	v_mov_b32_e32 v15, v0
	s_waitcnt vmcnt(1)
	v_fma_f32 v2, v16, v2, v28
	v_fmac_f32_e32 v2, v19, v3
	v_fmac_f32_e32 v2, v42, v4
	v_fmac_f32_e32 v2, v43, v5
	s_waitcnt vmcnt(0)
	v_fmac_f32_e32 v2, v44, v8
	v_mul_f32_e32 v2, v2, v9
	v_cvt_pk_bf16_f32 v4, v2, s0
	s_lshl_b64 s[0:1], s[14:15], 12
	s_add_u32 s0, s82, s0
	s_addc_u32 s1, s83, s1
	v_lshl_add_u64 v[2:3], s[0:1], 0, v[40:41]
	global_store_short v[2:3], v4, off offset:2048
	global_load_dwordx4 v[2:5], v[36:37], off offset:2560
	s_nop 0
	global_load_dwordx2 v[8:9], v[36:37], off offset:2576
	s_waitcnt vmcnt(1)
	v_fma_f32 v2, v16, v2, v29
	v_fmac_f32_e32 v2, v19, v3
	v_fmac_f32_e32 v2, v42, v4
	v_fmac_f32_e32 v2, v43, v5
	s_waitcnt vmcnt(0)
	v_fmac_f32_e32 v2, v44, v8
	v_fmac_f32_e32 v2, v17, v9
	v_mul_f32_e32 v2, v2, v10
	v_cvt_pk_bf16_f32 v4, v2, s0
	s_lshl_b64 s[0:1], s[16:17], 12
	s_add_u32 s0, s82, s0
	s_addc_u32 s1, s83, s1
	v_lshl_add_u64 v[2:3], s[0:1], 0, v[40:41]
	global_store_short v[2:3], v4, off offset:2048
	global_load_dwordx4 v[2:5], v[36:37], off offset:3072
	s_nop 0
	global_load_dwordx3 v[8:10], v[36:37], off offset:3088
	s_waitcnt vmcnt(1)
	v_fma_f32 v2, v16, v2, v30
	v_fmac_f32_e32 v2, v19, v3
	v_fmac_f32_e32 v2, v42, v4
	v_fmac_f32_e32 v2, v43, v5
	s_waitcnt vmcnt(0)
	v_fmac_f32_e32 v2, v44, v8
	v_fmac_f32_e32 v2, v17, v9
	v_fmac_f32_e32 v2, v18, v10
	v_mul_f32_e32 v2, v2, v11
	v_cvt_pk_bf16_f32 v4, v2, s0
	s_lshl_b64 s[0:1], s[18:19], 12
	s_add_u32 s0, s82, s0
	s_addc_u32 s1, s83, s1
	v_lshl_add_u64 v[2:3], s[0:1], 0, v[40:41]
	global_store_short v[2:3], v4, off offset:2048
	global_load_dwordx4 v[2:5], v[36:37], off offset:3584
	s_nop 0
	global_load_dwordx4 v[8:11], v[36:37], off offset:3600
	s_lshl_b64 s[0:1], s[20:21], 12
	s_add_u32 s0, s82, s0
	s_addc_u32 s1, s83, s1
	v_lshl_add_u64 v[12:13], s[0:1], 0, v[40:41]
	s_waitcnt vmcnt(1)
	v_fmac_f32_e32 v31, v16, v2
	v_fmac_f32_e32 v31, v19, v3
	v_fmac_f32_e32 v31, v42, v4
	v_fmac_f32_e32 v31, v43, v5
	s_waitcnt vmcnt(0)
	v_fmac_f32_e32 v31, v44, v8
	v_fmac_f32_e32 v31, v17, v9
	v_fmac_f32_e32 v31, v18, v10
	v_fmac_f32_e32 v31, v35, v11
	v_mul_f32_e32 v2, v31, v14
	v_cvt_pk_bf16_f32 v2, v2, s0
	global_store_short v[12:13], v2, off offset:2048
	s_barrier
	s_nop 0
	v_cmp_eq_u32_e32 vcc, 0, v15
	s_and_saveexec_b64 s[0:1], vcc
	s_cbranch_execz .LBB0_1248
	s_mov_b64 s[6:7], exec
	v_mbcnt_lo_u32_b32 v2, s6, 0
	v_mbcnt_hi_u32_b32 v2, s7, v2
	v_cmp_eq_u32_e32 vcc, 0, v2
	s_and_saveexec_b64 s[4:5], vcc
	s_cbranch_execz .LBB0_1247
	s_bcnt1_i32_b64 s6, s[6:7]
	v_mov_b32_e32 v3, s6
	v_mov_b32_e32 v254, v3
	v_mov_b32_e32 v3, v253
	s_nop 0
	global_atomic_add v253, v1, v254, s[54:55] sc0
	s_branch .LBB0_1247
